# v20 + grid barrier: last-arriving XCD leader bumps 16 per-XCD release flags itself; non-leader WGs poll their XCD's flag (32 pollers per word, one fewer hop than baseline)
# speedup vs baseline: 1.0006x; 1.0006x over previous
; __device__ __forceinline__ unsigned xb_ld(unsigned* p)              { return __hip_atomic_load(p, __ATOMIC_RELAXED, __HIP_MEMORY_SCOPE_AGENT); }
; __device__ __forceinline__ unsigned xb_add(unsigned* p, unsigned v) { return __hip_atomic_fetch_add(p, v, __ATOMIC_RELAXED, __HIP_MEMORY_SCOPE_AGENT); }
; #define XB_SPIN(cond, bar) do { unsigned _sp = 0; while (cond) { __builtin_amdgcn_s_sleep(1); \
;     if ((++_sp & 255u) == 0u) { if (xb_ld(&(bar)[XB_TMO])) break; if (_sp > XB_SPIN_CAP) { atomicAdd(&(bar)[XB_TMO], 1u); break; } } } } while (0)
; __device__ __forceinline__ void xcd_barrier(const XcdBarrier& b, const int wid) {
;     ...
;         const unsigned old = xb_add(&bar[XB_XSUB(b.x)], 1u);
;         const unsigned gen = old / nloc;
;         if (old + 1u == (gen + 1u) * nloc) {
;             __builtin_amdgcn_fence(__ATOMIC_RELEASE, "agent");
;             asm volatile("s_waitcnt vmcnt(0)" ::: "memory");
;             const unsigned og = xb_add(&bar[XB_TOP], 1u);
;             const unsigned tg = og / nx;
;             if (og + 1u == (tg + 1u) * nx) xb_add(&bar[XB_TOPGEN], 1u);
;             else XB_SPIN(xb_ld(&bar[XB_TOPGEN]) == tg, bar);
;             __builtin_amdgcn_fence(__ATOMIC_ACQUIRE, "agent");
;             xb_add(&bar[XB_XGEN(b.x)], 1u);
;             asm volatile("s_waitcnt vmcnt(0)" ::: "memory");
;         } else {
;             XB_SPIN(xb_ld(&bar[XB_XGEN(b.x)]) == gen, bar);
.LBB0_327:
	s_or_b64 exec, exec, s[12:13]
	v_cvt_f32_u32_e32 v4, v2
	s_waitcnt vmcnt(0)
	v_readfirstlane_b32 s3, v3
	v_sub_u32_e32 v3, 0, v2
	v_rcp_iflag_f32_e32 v4, v4
	v_add_u32_e32 v5, s3, v1
	v_mul_f32_e32 v4, 0x4f7ffffe, v4
	v_cvt_u32_f32_e32 v4, v4
	v_mul_lo_u32 v1, v3, v4
	v_mul_hi_u32 v1, v4, v1
	v_add_u32_e32 v1, v4, v1
	v_mul_hi_u32 v1, v5, v1
	v_mul_lo_u32 v3, v1, v2
	v_sub_u32_e32 v3, v5, v3
	v_add_u32_e32 v4, 1, v1
	v_cmp_ge_u32_e32 vcc, v3, v2
	s_nop 1
	v_cndmask_b32_e32 v1, v1, v4, vcc
	v_sub_u32_e32 v4, v3, v2
	v_cndmask_b32_e32 v3, v3, v4, vcc
	v_add_u32_e32 v4, 1, v1
	v_cmp_ge_u32_e32 vcc, v3, v2
	v_add_u32_e32 v3, 1, v5
	s_nop 0
	v_cndmask_b32_e32 v1, v1, v4, vcc
	v_mul_lo_u32 v4, v2, v1
	v_add_u32_e32 v2, v4, v2
	v_cmp_ne_u32_e32 vcc, v3, v2
	s_and_saveexec_b64 s[10:11], vcc
	s_xor_b64 s[10:11], exec, s[10:11]
	s_cbranch_execz .LBB0_341
	s_waitcnt lgkmcnt(0)
	v_mov_b32_e32 v0, 0x480
	global_load_dword v0, v0, s[8:9] sc1
	s_add_u32 s16, s8, 0x480
	s_addc_u32 s17, s9, 0
	s_waitcnt vmcnt(0)
	v_cmp_eq_u32_e32 vcc, v0, v1
	s_and_saveexec_b64 s[12:13], vcc
	s_cbranch_execz .LBB0_340
	s_add_u32 s14, s46, 0x4200
	s_addc_u32 s15, s47, 0
	s_mov_b32 s3, 1
	s_mov_b64 s[18:19], 0
	v_mov_b32_e32 v0, 0
	s_branch .LBB0_331

; __device__ __forceinline__ unsigned xb_ld(unsigned* p)              { return __hip_atomic_load(p, __ATOMIC_RELAXED, __HIP_MEMORY_SCOPE_AGENT); }
; __device__ __forceinline__ unsigned xb_add(unsigned* p, unsigned v) { return __hip_atomic_fetch_add(p, v, __ATOMIC_RELAXED, __HIP_MEMORY_SCOPE_AGENT); }
; #define XB_SPIN(cond, bar) do { unsigned _sp = 0; while (cond) { __builtin_amdgcn_s_sleep(1); \
;     if ((++_sp & 255u) == 0u) { if (xb_ld(&(bar)[XB_TMO])) break; if (_sp > XB_SPIN_CAP) { atomicAdd(&(bar)[XB_TMO], 1u); break; } } } } while (0)
; __device__ __forceinline__ void xcd_barrier(const XcdBarrier& b, const int wid) {
;     ...
;         const unsigned old = xb_add(&bar[XB_XSUB(b.x)], 1u);
;         const unsigned gen = old / nloc;
;         if (old + 1u == (gen + 1u) * nloc) {
;             __builtin_amdgcn_fence(__ATOMIC_RELEASE, "agent");
;             asm volatile("s_waitcnt vmcnt(0)" ::: "memory");
;             const unsigned og = xb_add(&bar[XB_TOP], 1u);
;             const unsigned tg = og / nx;
;             if (og + 1u == (tg + 1u) * nx) xb_add(&bar[XB_TOPGEN], 1u);
;             else XB_SPIN(xb_ld(&bar[XB_TOPGEN]) == tg, bar);
.LBB0_344:
	s_or_b64 exec, exec, s[12:13]
	v_cvt_f32_u32_e32 v3, v0
	s_waitcnt vmcnt(0)
	v_readfirstlane_b32 s3, v2
	s_add_u32 s12, s46, 0x7500
	s_addc_u32 s13, s47, 0
	v_rcp_iflag_f32_e32 v3, v3
	v_add_u32_e32 v1, s3, v1
	v_add_u32_e32 v4, 1, v1
	s_mov_b64 s[14:15], -1
	v_mul_f32_e32 v2, 0x4f7ffffe, v3
	v_cvt_u32_f32_e32 v2, v2
	v_sub_u32_e32 v3, 0, v0
	v_mul_lo_u32 v3, v3, v2
	v_mul_hi_u32 v3, v2, v3
	v_add_u32_e32 v2, v2, v3
	v_mul_hi_u32 v2, v1, v2
	v_mul_lo_u32 v3, v2, v0
	v_sub_u32_e32 v1, v1, v3
	v_add_u32_e32 v5, 1, v2
	v_cmp_ge_u32_e32 vcc, v1, v0
	v_sub_u32_e32 v3, v1, v0
	s_nop 0
	v_cndmask_b32_e32 v2, v2, v5, vcc
	v_cndmask_b32_e32 v1, v1, v3, vcc
	v_add_u32_e32 v3, 1, v2
	v_cmp_ge_u32_e32 vcc, v1, v0
	s_nop 1
	v_cndmask_b32_e32 v2, v2, v3, vcc
	v_mul_lo_u32 v1, v0, v2
	v_add_u32_e32 v0, v1, v0
	v_cmp_ne_u32_e32 vcc, v4, v0
	s_cbranch_vccnz .Lxbar_notlast_0
	v_mov_b32_e32 v16, 0x4480
	v_mov_b32_e32 v17, 1
	global_atomic_add v16, v17, s[46:47]
	global_atomic_add v16, v17, s[46:47] offset:256
	global_atomic_add v16, v17, s[46:47] offset:512
	global_atomic_add v16, v17, s[46:47] offset:768
	global_atomic_add v16, v17, s[46:47] offset:1024
	global_atomic_add v16, v17, s[46:47] offset:1280
	global_atomic_add v16, v17, s[46:47] offset:1536
	global_atomic_add v16, v17, s[46:47] offset:1792
	global_atomic_add v16, v17, s[46:47] offset:2048
	global_atomic_add v16, v17, s[46:47] offset:2304
	global_atomic_add v16, v17, s[46:47] offset:2560
	global_atomic_add v16, v17, s[46:47] offset:2816
	global_atomic_add v16, v17, s[46:47] offset:3072
	global_atomic_add v16, v17, s[46:47] offset:3328
	global_atomic_add v16, v17, s[46:47] offset:3584
	global_atomic_add v16, v17, s[46:47] offset:3840
.Lxbar_notlast_0:
	v_mov_b64_e32 v[0:1], s[12:13]
	s_and_saveexec_b64 s[10:11], vcc
	s_cbranch_execz .LBB0_356
	v_mov_b32_e32 v0, 0
	global_load_dword v1, v0, s[12:13] sc1
	s_mov_b64 s[18:19], 0
	s_waitcnt vmcnt(0)
	v_cmp_eq_u32_e32 vcc, v1, v2
	s_and_saveexec_b64 s[16:17], vcc
	s_cbranch_execz .LBB0_355
	s_add_u32 s14, s46, 0x4200
	s_addc_u32 s15, s47, 0
	s_mov_b32 s3, 1
	s_branch .LBB0_348

; __device__ __forceinline__ unsigned xb_ld(unsigned* p)              { return __hip_atomic_load(p, __ATOMIC_RELAXED, __HIP_MEMORY_SCOPE_AGENT); }
; __device__ __forceinline__ unsigned xb_add(unsigned* p, unsigned v) { return __hip_atomic_fetch_add(p, v, __ATOMIC_RELAXED, __HIP_MEMORY_SCOPE_AGENT); }
; #define XB_SPIN(cond, bar) do { unsigned _sp = 0; while (cond) { __builtin_amdgcn_s_sleep(1); \
;     if ((++_sp & 255u) == 0u) { if (xb_ld(&(bar)[XB_TMO])) break; if (_sp > XB_SPIN_CAP) { atomicAdd(&(bar)[XB_TMO], 1u); break; } } } } while (0)
; __device__ __forceinline__ void xcd_barrier(const XcdBarrier& b, const int wid) {
;     ...
;         const unsigned old = xb_add(&bar[XB_XSUB(b.x)], 1u);
;         const unsigned gen = old / nloc;
;         if (old + 1u == (gen + 1u) * nloc) {
;             __builtin_amdgcn_fence(__ATOMIC_RELEASE, "agent");
;             asm volatile("s_waitcnt vmcnt(0)" ::: "memory");
;             const unsigned og = xb_add(&bar[XB_TOP], 1u);
;             const unsigned tg = og / nx;
;             if (og + 1u == (tg + 1u) * nx) xb_add(&bar[XB_TOPGEN], 1u);
;             else XB_SPIN(xb_ld(&bar[XB_TOPGEN]) == tg, bar);
;             __builtin_amdgcn_fence(__ATOMIC_ACQUIRE, "agent");
;             xb_add(&bar[XB_XGEN(b.x)], 1u);
;             asm volatile("s_waitcnt vmcnt(0)" ::: "memory");
;         } else {
;             XB_SPIN(xb_ld(&bar[XB_XGEN(b.x)]) == gen, bar);
.LBB0_2184:
	s_or_b64 exec, exec, s[14:15]
	v_cvt_f32_u32_e32 v4, v2
	s_waitcnt vmcnt(0)
	v_readfirstlane_b32 s3, v3
	v_sub_u32_e32 v3, 0, v2
	v_rcp_iflag_f32_e32 v4, v4
	v_add_u32_e32 v5, s3, v1
	v_mul_f32_e32 v4, 0x4f7ffffe, v4
	v_cvt_u32_f32_e32 v4, v4
	v_mul_lo_u32 v1, v3, v4
	v_mul_hi_u32 v1, v4, v1
	v_add_u32_e32 v1, v4, v1
	v_mul_hi_u32 v1, v5, v1
	v_mul_lo_u32 v3, v1, v2
	v_sub_u32_e32 v3, v5, v3
	v_add_u32_e32 v4, 1, v1
	v_cmp_ge_u32_e32 vcc, v3, v2
	s_nop 1
	v_cndmask_b32_e32 v1, v1, v4, vcc
	v_sub_u32_e32 v4, v3, v2
	v_cndmask_b32_e32 v3, v3, v4, vcc
	v_add_u32_e32 v4, 1, v1
	v_cmp_ge_u32_e32 vcc, v3, v2
	v_add_u32_e32 v3, 1, v5
	s_nop 0
	v_cndmask_b32_e32 v1, v1, v4, vcc
	v_mul_lo_u32 v4, v2, v1
	v_add_u32_e32 v2, v4, v2
	v_cmp_ne_u32_e32 vcc, v3, v2
	s_and_saveexec_b64 s[12:13], vcc
	s_xor_b64 s[12:13], exec, s[12:13]
	s_cbranch_execz .LBB0_2198
	s_waitcnt lgkmcnt(0)
	v_mov_b32_e32 v0, 0x480
	global_load_dword v0, v0, s[10:11] sc1
	s_add_u32 s18, s10, 0x480
	s_addc_u32 s19, s11, 0
	s_waitcnt vmcnt(0)
	v_cmp_eq_u32_e32 vcc, v0, v1
	s_and_saveexec_b64 s[14:15], vcc
	s_cbranch_execz .LBB0_2197
	s_add_u32 s16, s46, 0x4200
	s_addc_u32 s17, s47, 0
	s_mov_b32 s3, 1
	s_mov_b64 s[20:21], 0
	v_mov_b32_e32 v0, 0
	s_branch .LBB0_2188

; __device__ __forceinline__ unsigned xb_ld(unsigned* p)              { return __hip_atomic_load(p, __ATOMIC_RELAXED, __HIP_MEMORY_SCOPE_AGENT); }
; __device__ __forceinline__ unsigned xb_add(unsigned* p, unsigned v) { return __hip_atomic_fetch_add(p, v, __ATOMIC_RELAXED, __HIP_MEMORY_SCOPE_AGENT); }
; #define XB_SPIN(cond, bar) do { unsigned _sp = 0; while (cond) { __builtin_amdgcn_s_sleep(1); \
;     if ((++_sp & 255u) == 0u) { if (xb_ld(&(bar)[XB_TMO])) break; if (_sp > XB_SPIN_CAP) { atomicAdd(&(bar)[XB_TMO], 1u); break; } } } } while (0)
; __device__ __forceinline__ void xcd_barrier(const XcdBarrier& b, const int wid) {
;     ...
;         const unsigned old = xb_add(&bar[XB_XSUB(b.x)], 1u);
;         const unsigned gen = old / nloc;
;         if (old + 1u == (gen + 1u) * nloc) {
;             __builtin_amdgcn_fence(__ATOMIC_RELEASE, "agent");
;             asm volatile("s_waitcnt vmcnt(0)" ::: "memory");
;             const unsigned og = xb_add(&bar[XB_TOP], 1u);
;             const unsigned tg = og / nx;
;             if (og + 1u == (tg + 1u) * nx) xb_add(&bar[XB_TOPGEN], 1u);
;             else XB_SPIN(xb_ld(&bar[XB_TOPGEN]) == tg, bar);
.LBB0_2201:
	s_or_b64 exec, exec, s[14:15]
	v_cvt_f32_u32_e32 v3, v0
	s_waitcnt vmcnt(0)
	v_readfirstlane_b32 s3, v2
	s_add_u32 s14, s46, 0x7500
	s_addc_u32 s15, s47, 0
	v_rcp_iflag_f32_e32 v3, v3
	v_add_u32_e32 v1, s3, v1
	v_add_u32_e32 v4, 1, v1
	s_mov_b64 s[16:17], -1
	v_mul_f32_e32 v2, 0x4f7ffffe, v3
	v_cvt_u32_f32_e32 v2, v2
	v_sub_u32_e32 v3, 0, v0
	v_mul_lo_u32 v3, v3, v2
	v_mul_hi_u32 v3, v2, v3
	v_add_u32_e32 v2, v2, v3
	v_mul_hi_u32 v2, v1, v2
	v_mul_lo_u32 v3, v2, v0
	v_sub_u32_e32 v1, v1, v3
	v_add_u32_e32 v5, 1, v2
	v_cmp_ge_u32_e32 vcc, v1, v0
	v_sub_u32_e32 v3, v1, v0
	s_nop 0
	v_cndmask_b32_e32 v2, v2, v5, vcc
	v_cndmask_b32_e32 v1, v1, v3, vcc
	v_add_u32_e32 v3, 1, v2
	v_cmp_ge_u32_e32 vcc, v1, v0
	s_nop 1
	v_cndmask_b32_e32 v2, v2, v3, vcc
	v_mul_lo_u32 v1, v0, v2
	v_add_u32_e32 v0, v1, v0
	v_cmp_ne_u32_e32 vcc, v4, v0
	s_cbranch_vccnz .Lxbar_notlast_4
	v_mov_b32_e32 v16, 0x4480
	v_mov_b32_e32 v17, 1
	global_atomic_add v16, v17, s[46:47]
	global_atomic_add v16, v17, s[46:47] offset:256
	global_atomic_add v16, v17, s[46:47] offset:512
	global_atomic_add v16, v17, s[46:47] offset:768
	global_atomic_add v16, v17, s[46:47] offset:1024
	global_atomic_add v16, v17, s[46:47] offset:1280
	global_atomic_add v16, v17, s[46:47] offset:1536
	global_atomic_add v16, v17, s[46:47] offset:1792
	global_atomic_add v16, v17, s[46:47] offset:2048
	global_atomic_add v16, v17, s[46:47] offset:2304
	global_atomic_add v16, v17, s[46:47] offset:2560
	global_atomic_add v16, v17, s[46:47] offset:2816
	global_atomic_add v16, v17, s[46:47] offset:3072
	global_atomic_add v16, v17, s[46:47] offset:3328
	global_atomic_add v16, v17, s[46:47] offset:3584
	global_atomic_add v16, v17, s[46:47] offset:3840
.Lxbar_notlast_4:
	v_mov_b64_e32 v[0:1], s[14:15]
	s_and_saveexec_b64 s[12:13], vcc
	s_cbranch_execz .LBB0_2213
	v_mov_b32_e32 v0, 0
	global_load_dword v1, v0, s[14:15] sc1
	s_mov_b64 s[20:21], 0
	s_waitcnt vmcnt(0)
	v_cmp_eq_u32_e32 vcc, v1, v2
	s_and_saveexec_b64 s[18:19], vcc
	s_cbranch_execz .LBB0_2212
	s_add_u32 s16, s46, 0x4200
	s_addc_u32 s17, s47, 0
	s_mov_b32 s3, 1
	s_branch .LBB0_2205

; __device__ __forceinline__ unsigned xb_ld(unsigned* p)              { return __hip_atomic_load(p, __ATOMIC_RELAXED, __HIP_MEMORY_SCOPE_AGENT); }
; __device__ __forceinline__ unsigned xb_add(unsigned* p, unsigned v) { return __hip_atomic_fetch_add(p, v, __ATOMIC_RELAXED, __HIP_MEMORY_SCOPE_AGENT); }
; #define XB_SPIN(cond, bar) do { unsigned _sp = 0; while (cond) { __builtin_amdgcn_s_sleep(1); \
;     if ((++_sp & 255u) == 0u) { if (xb_ld(&(bar)[XB_TMO])) break; if (_sp > XB_SPIN_CAP) { atomicAdd(&(bar)[XB_TMO], 1u); break; } } } } while (0)
; __device__ __forceinline__ void xcd_barrier(const XcdBarrier& b, const int wid) {
;     ...
;         const unsigned old = xb_add(&bar[XB_XSUB(b.x)], 1u);
;         const unsigned gen = old / nloc;
;         if (old + 1u == (gen + 1u) * nloc) {
;             __builtin_amdgcn_fence(__ATOMIC_RELEASE, "agent");
;             asm volatile("s_waitcnt vmcnt(0)" ::: "memory");
;             const unsigned og = xb_add(&bar[XB_TOP], 1u);
;             const unsigned tg = og / nx;
;             if (og + 1u == (tg + 1u) * nx) xb_add(&bar[XB_TOPGEN], 1u);
;             else XB_SPIN(xb_ld(&bar[XB_TOPGEN]) == tg, bar);
;             __builtin_amdgcn_fence(__ATOMIC_ACQUIRE, "agent");
;             xb_add(&bar[XB_XGEN(b.x)], 1u);
;             asm volatile("s_waitcnt vmcnt(0)" ::: "memory");
;         } else {
;             XB_SPIN(xb_ld(&bar[XB_XGEN(b.x)]) == gen, bar);
.LBB0_2567:
	s_or_b64 exec, exec, s[10:11]
	v_cvt_f32_u32_e32 v4, v2
	s_waitcnt vmcnt(0)
	v_readfirstlane_b32 s8, v3
	v_sub_u32_e32 v3, 0, v2
	v_rcp_iflag_f32_e32 v4, v4
	v_add_u32_e32 v5, s8, v1
	v_mul_f32_e32 v4, 0x4f7ffffe, v4
	v_cvt_u32_f32_e32 v4, v4
	v_mul_lo_u32 v1, v3, v4
	v_mul_hi_u32 v1, v4, v1
	v_add_u32_e32 v1, v4, v1
	v_mul_hi_u32 v1, v5, v1
	v_mul_lo_u32 v3, v1, v2
	v_sub_u32_e32 v3, v5, v3
	v_add_u32_e32 v4, 1, v1
	v_cmp_ge_u32_e32 vcc, v3, v2
	s_nop 1
	v_cndmask_b32_e32 v1, v1, v4, vcc
	v_sub_u32_e32 v4, v3, v2
	v_cndmask_b32_e32 v3, v3, v4, vcc
	v_add_u32_e32 v4, 1, v1
	v_cmp_ge_u32_e32 vcc, v3, v2
	v_add_u32_e32 v3, 1, v5
	s_nop 0
	v_cndmask_b32_e32 v1, v1, v4, vcc
	v_mul_lo_u32 v4, v2, v1
	v_add_u32_e32 v2, v4, v2
	v_cmp_ne_u32_e32 vcc, v3, v2
	s_and_saveexec_b64 s[8:9], vcc
	s_xor_b64 s[8:9], exec, s[8:9]
	s_cbranch_execz .LBB0_2581
	s_waitcnt lgkmcnt(0)
	v_mov_b32_e32 v0, 0x480
	global_load_dword v0, v0, s[6:7] sc1
	s_add_u32 s14, s6, 0x480
	s_addc_u32 s15, s7, 0
	s_waitcnt vmcnt(0)
	v_cmp_eq_u32_e32 vcc, v0, v1
	s_and_saveexec_b64 s[10:11], vcc
	s_cbranch_execz .LBB0_2580
	s_add_u32 s12, s46, 0x4200
	s_addc_u32 s13, s47, 0
	s_mov_b32 s26, 1
	s_mov_b64 s[16:17], 0
	v_mov_b32_e32 v0, 0
	s_branch .LBB0_2571

; __device__ __forceinline__ unsigned xb_ld(unsigned* p)              { return __hip_atomic_load(p, __ATOMIC_RELAXED, __HIP_MEMORY_SCOPE_AGENT); }
; __device__ __forceinline__ unsigned xb_add(unsigned* p, unsigned v) { return __hip_atomic_fetch_add(p, v, __ATOMIC_RELAXED, __HIP_MEMORY_SCOPE_AGENT); }
; #define XB_SPIN(cond, bar) do { unsigned _sp = 0; while (cond) { __builtin_amdgcn_s_sleep(1); \
;     if ((++_sp & 255u) == 0u) { if (xb_ld(&(bar)[XB_TMO])) break; if (_sp > XB_SPIN_CAP) { atomicAdd(&(bar)[XB_TMO], 1u); break; } } } } while (0)
; __device__ __forceinline__ void xcd_barrier(const XcdBarrier& b, const int wid) {
;     ...
;         const unsigned old = xb_add(&bar[XB_XSUB(b.x)], 1u);
;         const unsigned gen = old / nloc;
;         if (old + 1u == (gen + 1u) * nloc) {
;             __builtin_amdgcn_fence(__ATOMIC_RELEASE, "agent");
;             asm volatile("s_waitcnt vmcnt(0)" ::: "memory");
;             const unsigned og = xb_add(&bar[XB_TOP], 1u);
;             const unsigned tg = og / nx;
;             if (og + 1u == (tg + 1u) * nx) xb_add(&bar[XB_TOPGEN], 1u);
;             else XB_SPIN(xb_ld(&bar[XB_TOPGEN]) == tg, bar);
.LBB0_2584:
	s_or_b64 exec, exec, s[10:11]
	v_cvt_f32_u32_e32 v3, v0
	s_waitcnt vmcnt(0)
	v_readfirstlane_b32 s8, v2
	s_add_u32 s10, s46, 0x7500
	s_addc_u32 s11, s47, 0
	v_rcp_iflag_f32_e32 v3, v3
	v_add_u32_e32 v1, s8, v1
	v_add_u32_e32 v4, 1, v1
	s_mov_b64 s[12:13], -1
	v_mul_f32_e32 v2, 0x4f7ffffe, v3
	v_cvt_u32_f32_e32 v2, v2
	v_sub_u32_e32 v3, 0, v0
	v_mul_lo_u32 v3, v3, v2
	v_mul_hi_u32 v3, v2, v3
	v_add_u32_e32 v2, v2, v3
	v_mul_hi_u32 v2, v1, v2
	v_mul_lo_u32 v3, v2, v0
	v_sub_u32_e32 v1, v1, v3
	v_add_u32_e32 v5, 1, v2
	v_cmp_ge_u32_e32 vcc, v1, v0
	v_sub_u32_e32 v3, v1, v0
	s_nop 0
	v_cndmask_b32_e32 v2, v2, v5, vcc
	v_cndmask_b32_e32 v1, v1, v3, vcc
	v_add_u32_e32 v3, 1, v2
	v_cmp_ge_u32_e32 vcc, v1, v0
	s_nop 1
	v_cndmask_b32_e32 v2, v2, v3, vcc
	v_mul_lo_u32 v1, v0, v2
	v_add_u32_e32 v0, v1, v0
	v_cmp_ne_u32_e32 vcc, v4, v0
	s_cbranch_vccnz .Lxbar_notlast_9
	v_mov_b32_e32 v16, 0x4480
	v_mov_b32_e32 v17, 1
	global_atomic_add v16, v17, s[46:47]
	global_atomic_add v16, v17, s[46:47] offset:256
	global_atomic_add v16, v17, s[46:47] offset:512
	global_atomic_add v16, v17, s[46:47] offset:768
	global_atomic_add v16, v17, s[46:47] offset:1024
	global_atomic_add v16, v17, s[46:47] offset:1280
	global_atomic_add v16, v17, s[46:47] offset:1536
	global_atomic_add v16, v17, s[46:47] offset:1792
	global_atomic_add v16, v17, s[46:47] offset:2048
	global_atomic_add v16, v17, s[46:47] offset:2304
	global_atomic_add v16, v17, s[46:47] offset:2560
	global_atomic_add v16, v17, s[46:47] offset:2816
	global_atomic_add v16, v17, s[46:47] offset:3072
	global_atomic_add v16, v17, s[46:47] offset:3328
	global_atomic_add v16, v17, s[46:47] offset:3584
	global_atomic_add v16, v17, s[46:47] offset:3840
.Lxbar_notlast_9:
	v_mov_b64_e32 v[0:1], s[10:11]
	s_and_saveexec_b64 s[8:9], vcc
	s_cbranch_execz .LBB0_2596
	v_mov_b32_e32 v0, 0
	global_load_dword v1, v0, s[10:11] sc1
	s_mov_b64 s[16:17], 0
	s_waitcnt vmcnt(0)
	v_cmp_eq_u32_e32 vcc, v1, v2
	s_and_saveexec_b64 s[14:15], vcc
	s_cbranch_execz .LBB0_2595
	s_add_u32 s12, s46, 0x4200
	s_addc_u32 s13, s47, 0
	s_mov_b32 s26, 1
	s_branch .LBB0_2588
